# MLA K/V/rope ring staged by LDS-DMA (global_load_lds_dwordx4 into the padded LDS images) instead of global_load->VGPR->ds_write_b128
# speedup vs baseline: 1.0071x; 1.0071x over previous
; DI float bfs2f(short v) { return __uint_as_float(((unsigned)(u16)v) << 16); }
; DI u16 f2bf(float a) { return (u16)(pk2(a, 0.f) & 0xffffu); }
; #define MLA_GLOAD(T) do { rkn = *(const u32x4*)(kvsrc + (size_t)(T) * 64 * KVP); rvv = *(const u32x4*)(kvsrc + (size_t)(T) * 64 * KVP + 64); \
;     if (kr_on) rkr = *(const u32x4*)(krsrc + (size_t)(T) * 64 * 32); } while (0)
; #define MLA_LSTORE(B) do { u16* kd = Kl + (B) * 64 * KP; u16* vd = Vl + (B) * 64 * VP; *(u32x4*)(kd + kdst0) = rkn; *(u32x4*)(vd + vdst) = rvv; \
;     if (kr_on) *(u32x4*)(kd + kdst2) = rkr; } while (0)
; DI void mla_unit(const Params& p, char* lds, int seqbase, int S, int h, int qb) {
;     ...
;   const int pos = qb * 256 + wid * 32 + r32, qrow = seqbase + pos;
;   bf16x8 qf[6];
; #pragma unroll
;   for (int d0 = 0; d0 < 6; ++d0) qf[d0] = *(const bf16x8*)(Q + (size_t)qrow * 1536 + h * 96 + d0 * 16 + 8 * hi);
;   const float C = 0.10206207261596577f * LOG2E;
; #pragma unroll
;   for (int j = 0; j < 8; ++j) {
;     const float c = ct[pos * 16 + 8 * hi + j], s = st[pos * 16 + 8 * hi + j];
;     const float t1 = bfs2f(qf[4][j]), t2 = bfs2f(qf[5][j]);
;     qf[4][j] = (short)f2bf((t1 * c - t2 * s) * C); qf[5][j] = (short)f2bf((t1 * s + t2 * c) * C);
;   }
; #pragma unroll
;   for (int d0 = 0; d0 < 4; ++d0)
; #pragma unroll
;     for (int j = 0; j < 8; ++j) qf[d0][j] = (short)f2bf(bfs2f(qf[d0][j]) * C);
;   const int srow = tid >> 3, sc = tid & 7, rrow = (tid >> 2) & 63, rc = tid & 3;
;   const bool kr_on = tid < 256;
;   const u16* kvsrc = KV + (size_t)(seqbase + srow) * KVP + h * 128 + sc * 8;
;   const u16* krsrc = KR + (size_t)(seqbase + rrow) * 32 + rc * 8;
;   const int kdst0 = srow * KP + sc * 8, kdst2 = rrow * KP + 64 + rc * 8, vdst = srow * VP + sc * 8;
;   float l_run = 0.f; f32x16 o0 = {}, o1 = {}, negm = {};
;   const int nkt = S >> 6;
;   u32x4 rkn, rkr, rvv;
;     ...
;   MLA_GLOAD(0); MLA_LSTORE(0);
;   MLA_GLOAD(1); MLA_LSTORE(1);
.LBB0_1064:
	s_min_i32 s48, s61, 0xff
	s_lshr_b32 s28, s48, 2
	s_and_b32 s28, s28, 8
	s_or_b32 s62, s28, s3
	s_lshl_b32 s28, s48, 7
	s_and_b32 s46, s28, 0xffffe000
	s_lshl_b32 s28, s48, 8
	s_and_b32 s28, s28, 0x1f00
	v_add_u32_e32 v0, s28, v175
	v_add_u32_e32 v168, s46, v0
	v_mad_i64_i32 v[2:3], s[28:29], v168, s58, v[164:165]
	s_mul_i32 s36, s62, 0xc0
	v_lshl_add_u64 v[2:3], v[2:3], 0, s[36:37]
	v_lshl_add_u64 v[18:19], v[2:3], 0, v[160:161]
	global_load_dwordx4 v[14:17], v[18:19], off
	global_load_dwordx4 v[10:13], v[18:19], off offset:32
	global_load_dwordx4 v[6:9], v[18:19], off offset:64
	global_load_dwordx4 v[2:5], v[18:19], off offset:96
	global_load_dwordx4 v[30:33], v[18:19], off offset:128
	global_load_dwordx4 v[26:29], v[18:19], off offset:160
	v_or_b32_e32 v56, s46, v176
	v_lshl_or_b32 v0, v0, 6, v185
	v_mad_i64_i32 v[42:43], s[28:29], v56, s59, v[166:167]
	s_lshl_b32 s36, s62, 8
	global_load_dwordx4 v[18:21], v0, s[10:11] offset:16
	global_load_dwordx4 v[34:37], v0, s[10:11]
	global_load_dwordx4 v[22:25], v0, s[14:15] offset:16
	global_load_dwordx4 v[38:41], v0, s[14:15]
	v_lshl_add_u64 v[42:43], v[42:43], 0, s[36:37]
	v_lshl_add_u64 v[54:55], v[42:43], 0, v[162:163]
	v_or_b32_e32 v50, s46, v177
	v_ashrrev_i32_e32 v51, 31, v50
	v_lshlrev_b64 v[52:53], 6, v[50:51]
	v_lshl_add_u64 v[52:53], v[154:155], 0, v[52:53]
	s_nop 1
	v_readfirstlane_b32 s96, v54
	v_readfirstlane_b32 s98, v52
	v_readfirstlane_b32 s100, v174
	s_lshr_b32 s100, s100, 6
	s_sub_u32 s96, s96, s24
	s_mul_i32 s101, s100, 0x8400
	s_sub_u32 s96, s96, s101
	s_sub_u32 s98, s98, s24
	s_lshl_b32 s101, s100, 4
	s_and_b32 s101, s101, 63
	s_lshl_b32 s101, s101, 6
	s_sub_u32 s98, s98, s101
	v_and_b32_e32 v206, 63, v174
	v_lshl_add_u32 v206, s100, 6, v206
	v_add_u32_e32 v207, 0x200, v206
	v_mul_u32_u24_e32 v208, 0x13b2, v206
	v_lshrrev_b32_e32 v208, 16, v208
	v_mul_u32_u24_e32 v209, 13, v208
	v_sub_u32_e32 v209, v206, v209
	v_mul_u32_u24_e32 v210, 0x1080, v208
	v_add_u32_e32 v210, s96, v210
	v_lshlrev_b32_e32 v211, 4, v209
	v_cmp_gt_u32_e32 vcc, 8, v209
	s_nop 1
	v_cndmask_b32_e32 v211, 0, v211, vcc
	v_add_u32_e32 v200, v210, v211
	v_lshlrev_b32_e32 v210, 6, v208
	v_add_u32_e32 v210, s98, v210
	v_add_u32_e32 v211, -8, v209
	v_lshl_add_u32 v210, v211, 4, v210
	v_cmp_gt_u32_e32 vcc, 4, v211
	s_nop 1
	v_cndmask_b32_e32 v200, v200, v210, vcc
	v_mov_b32_e32 v211, 0x1000
	v_mov_b32_e32 v201, 0x42000
	v_cndmask_b32_e32 v201, v201, v211, vcc
	v_mul_u32_u24_e32 v208, 0x13b2, v207
	v_lshrrev_b32_e32 v208, 16, v208
	v_mul_u32_u24_e32 v209, 13, v208
	v_sub_u32_e32 v209, v207, v209
	v_mul_u32_u24_e32 v210, 0x1080, v208
	v_add_u32_e32 v210, s96, v210
	v_lshlrev_b32_e32 v211, 4, v209
	v_cmp_gt_u32_e32 vcc, 8, v209
	s_nop 1
	v_cndmask_b32_e32 v211, 0, v211, vcc
	v_add_u32_e32 v202, v210, v211
	v_lshlrev_b32_e32 v210, 6, v208
	v_add_u32_e32 v210, s98, v210
	v_add_u32_e32 v211, -8, v209
	v_lshl_add_u32 v210, v211, 4, v210
	v_cmp_gt_u32_e32 vcc, 4, v211
	s_nop 1
	v_cndmask_b32_e32 v202, v202, v210, vcc
	v_mov_b32_e32 v211, 0x1000
	v_mov_b32_e32 v203, 0x42000
	v_cndmask_b32_e32 v203, v203, v211, vcc
	v_mul_u32_u24_e32 v208, 0x1556, v206
	v_lshrrev_b32_e32 v208, 16, v208
	v_mul_u32_u24_e32 v209, 12, v208
	v_sub_u32_e32 v209, v206, v209
	v_min_u32_e32 v209, 7, v209
	v_mul_u32_u24_e32 v210, 0x1080, v208
	v_add_u32_e32 v210, s96, v210
	v_lshl_add_u32 v210, v209, 4, v210
	v_add_u32_e32 v204, 0x80, v210
	v_mul_u32_u24_e32 v208, 0x1556, v207
	v_lshrrev_b32_e32 v208, 16, v208
	v_mul_u32_u24_e32 v209, 12, v208
	v_sub_u32_e32 v209, v207, v209
	v_min_u32_e32 v209, 7, v209
	v_mul_u32_u24_e32 v210, 0x1080, v208
	v_add_u32_e32 v210, s96, v210
	v_lshl_add_u32 v210, v209, 4, v210
	v_add_u32_e32 v205, 0x80, v210
	s_mov_b32 s96, 0
	s_mov_b32 s98, 0x9c00
	s_lshl_b32 s101, s100, 10
	s_add_u32 m0, s96, s101
	s_nop 0
	global_load_lds_dwordx4 v200, s[24:25]
	v_add_u32_e32 v200, v200, v201
	s_cmp_lt_u32 s100, 5
	s_cbranch_scc0 .Lmd_skb4
	s_add_u32 m0, m0, 0x2000
	s_nop 0
	global_load_lds_dwordx4 v202, s[24:25]
	v_add_u32_e32 v202, v202, v203
.Lmd_skb4:
	s_add_u32 m0, s98, s101
	s_nop 0
	global_load_lds_dwordx4 v204, s[24:25]
	v_add_u32_e32 v204, 0x42000, v204
	s_cmp_lt_u32 s100, 4
	s_cbranch_scc0 .Lmd_svb4
	s_add_u32 m0, m0, 0x2000
	s_nop 0
	global_load_lds_dwordx4 v205, s[24:25]
	v_add_u32_e32 v205, 0x42000, v205
.Lmd_svb4:
	s_mov_b32 s96, 0x3400
	s_mov_b32 s98, 0xcc00
	s_lshl_b32 s101, s100, 10
	s_add_u32 m0, s96, s101
	s_nop 0
	global_load_lds_dwordx4 v200, s[24:25]
	v_add_u32_e32 v200, v200, v201
	s_cmp_lt_u32 s100, 5
	s_cbranch_scc0 .Lmd_skb5
	s_add_u32 m0, m0, 0x2000
	s_nop 0
	global_load_lds_dwordx4 v202, s[24:25]
	v_add_u32_e32 v202, v202, v203

; DI float bfs2f(short v) { return __uint_as_float(((unsigned)(u16)v) << 16); }
; DI u16 f2bf(float a) { return (u16)(pk2(a, 0.f) & 0xffffu); }
; #define MLA_GLOAD(T) do { rkn = *(const u32x4*)(kvsrc + (size_t)(T) * 64 * KVP); rvv = *(const u32x4*)(kvsrc + (size_t)(T) * 64 * KVP + 64); \
;     if (kr_on) rkr = *(const u32x4*)(krsrc + (size_t)(T) * 64 * 32); } while (0)
; #define MLA_LSTORE(B) do { u16* kd = Kl + (B) * 64 * KP; u16* vd = Vl + (B) * 64 * VP; *(u32x4*)(kd + kdst0) = rkn; *(u32x4*)(vd + vdst) = rvv; \
;     if (kr_on) *(u32x4*)(kd + kdst2) = rkr; } while (0)
; DI void mla_unit(const Params& p, char* lds, int seqbase, int S, int h, int qb) {
;     ...
;   const float C = 0.10206207261596577f * LOG2E;
; #pragma unroll
;   for (int j = 0; j < 8; ++j) {
;     const float c = ct[pos * 16 + 8 * hi + j], s = st[pos * 16 + 8 * hi + j];
;     const float t1 = bfs2f(qf[4][j]), t2 = bfs2f(qf[5][j]);
;     qf[4][j] = (short)f2bf((t1 * c - t2 * s) * C); qf[5][j] = (short)f2bf((t1 * s + t2 * c) * C);
;   }
; #pragma unroll
;   for (int d0 = 0; d0 < 4; ++d0)
; #pragma unroll
;     for (int j = 0; j < 8; ++j) qf[d0][j] = (short)f2bf(bfs2f(qf[d0][j]) * C);
;   const int srow = tid >> 3, sc = tid & 7, rrow = (tid >> 2) & 63, rc = tid & 3;
;   const bool kr_on = tid < 256;
;   const u16* kvsrc = KV + (size_t)(seqbase + srow) * KVP + h * 128 + sc * 8;
;   const u16* krsrc = KR + (size_t)(seqbase + rrow) * 32 + rc * 8;
;   const int kdst0 = srow * KP + sc * 8, kdst2 = rrow * KP + 64 + rc * 8, vdst = srow * VP + sc * 8;
;   float l_run = 0.f; f32x16 o0 = {}, o1 = {}, negm = {};
;   const int nkt = S >> 6;
;   u32x4 rkn, rkr, rvv;
;     ...
;   MLA_GLOAD(0); MLA_LSTORE(0);
;   MLA_GLOAD(1); MLA_LSTORE(1);
;   __syncthreads();
;   int cur = 0, nx2 = 2;
;   if (wid >= 4) __builtin_amdgcn_s_setprio(1);
.Lmd_svb5:
	s_waitcnt vmcnt(0)
	s_waitcnt lgkmcnt(0)
	s_barrier
	s_and_saveexec_b64 s[46:47], s[4:5]
	s_setprio 1
	s_or_b64 exec, exec, s[46:47]
	s_lshl_b32 s28, s48, 6
	s_and_b32 s28, s28, 0x800
	s_or_b32 s28, s28, s57
	v_lshlrev_b64 v[42:43], 6, v[50:51]
	v_mov_b32_e32 v0, s28
	v_lshl_add_u64 v[170:171], v[156:157], 0, v[42:43]
	v_mad_i64_i32 v[42:43], s[28:29], v56, s59, v[0:1]
	v_and_b32_e32 v45, 0xffff0000, v26
	v_lshlrev_b32_e32 v44, 16, v26
	v_lshl_add_u64 v[172:173], v[158:159], 0, v[42:43]
	v_and_b32_e32 v43, 0xffff0000, v30
	v_lshlrev_b32_e32 v42, 16, v30
	v_pk_mul_f32 v[46:47], v[34:35], v[44:45]
	v_lshlrev_b32_e32 v30, 16, v27
	v_pk_fma_f32 v[46:47], v[38:39], v[42:43], v[46:47]
	v_pk_mul_f32 v[38:39], v[38:39], v[44:45]
	v_pk_mul_f32 v[46:47], v[46:47], s[38:39] op_sel_hi:[1,0]
	v_pk_fma_f32 v[34:35], v[34:35], v[42:43], v[38:39] neg_lo:[0,0,1] neg_hi:[0,0,1]
	v_cvt_pk_bf16_f32 v108, v46, v47
	v_pk_mul_f32 v[34:35], v[34:35], s[38:39] op_sel_hi:[1,0]
	v_mov_b32_e32 v0, v1
	v_cvt_pk_bf16_f32 v112, v34, v35
	v_and_b32_e32 v35, 0xffff0000, v31
	v_lshlrev_b32_e32 v34, 16, v31
	v_and_b32_e32 v31, 0xffff0000, v27
	v_pk_mul_f32 v[26:27], v[40:41], v[34:35]
	v_ashrrev_i32_e32 v169, 31, v168
	v_pk_fma_f32 v[26:27], v[36:37], v[30:31], v[26:27]
	s_mov_b32 s36, 0
	v_pk_mul_f32 v[26:27], v[26:27], s[38:39] op_sel_hi:[1,0]
	s_mov_b32 s63, 2
	v_cvt_pk_bf16_f32 v109, v26, v27
	v_pk_mul_f32 v[26:27], v[40:41], v[30:31]
	v_and_b32_e32 v31, 0xffff0000, v28
	v_pk_fma_f32 v[26:27], v[36:37], v[34:35], v[26:27] neg_lo:[0,0,1] neg_hi:[0,0,1]
	v_lshlrev_b32_e32 v30, 16, v28
	v_pk_mul_f32 v[26:27], v[26:27], s[38:39] op_sel_hi:[1,0]
	v_mov_b32_e32 v153, 0
	v_cvt_pk_bf16_f32 v113, v26, v27
	v_and_b32_e32 v27, 0xffff0000, v32
	v_lshlrev_b32_e32 v26, 16, v32
	v_pk_mul_f32 v[34:35], v[22:23], v[26:27]
	v_pk_mul_f32 v[22:23], v[22:23], v[30:31]
	v_pk_fma_f32 v[34:35], v[18:19], v[30:31], v[34:35]
	v_pk_fma_f32 v[18:19], v[18:19], v[26:27], v[22:23] neg_lo:[0,0,1] neg_hi:[0,0,1]
	v_and_b32_e32 v23, 0xffff0000, v29
	v_pk_mul_f32 v[18:19], v[18:19], s[38:39] op_sel_hi:[1,0]
	v_lshlrev_b32_e32 v22, 16, v29
	v_cvt_pk_bf16_f32 v114, v18, v19
	v_and_b32_e32 v19, 0xffff0000, v33
	v_lshlrev_b32_e32 v18, 16, v33
	v_pk_mul_f32 v[26:27], v[24:25], v[18:19]
	v_pk_mul_f32 v[34:35], v[34:35], s[38:39] op_sel_hi:[1,0]
	v_pk_fma_f32 v[26:27], v[20:21], v[22:23], v[26:27]
	v_pk_mul_f32 v[22:23], v[24:25], v[22:23]
	v_pk_mul_f32 v[26:27], v[26:27], s[38:39] op_sel_hi:[1,0]
	v_pk_fma_f32 v[18:19], v[20:21], v[18:19], v[22:23] neg_lo:[0,0,1] neg_hi:[0,0,1]
	v_cvt_pk_bf16_f32 v110, v34, v35
	v_pk_mul_f32 v[18:19], v[18:19], s[38:39] op_sel_hi:[1,0]
	v_cvt_pk_bf16_f32 v111, v26, v27
	v_cvt_pk_bf16_f32 v115, v18, v19
	v_and_b32_e32 v19, 0xffff0000, v14
	v_lshlrev_b32_e32 v18, 16, v14
	v_pk_mul_f32 v[18:19], v[18:19], s[38:39] op_sel_hi:[1,0]
	s_mov_b64 s[46:47], 0
	v_cvt_pk_bf16_f32 v116, v18, v19
	v_and_b32_e32 v19, 0xffff0000, v15
	v_lshlrev_b32_e32 v18, 16, v15
	v_pk_mul_f32 v[14:15], v[18:19], s[38:39] op_sel_hi:[1,0]
	s_mov_b32 s64, 0
	v_cvt_pk_bf16_f32 v117, v14, v15
	v_and_b32_e32 v15, 0xffff0000, v16
	v_lshlrev_b32_e32 v14, 16, v16
	v_pk_mul_f32 v[14:15], v[14:15], s[38:39] op_sel_hi:[1,0]
	s_nop 0
	v_cvt_pk_bf16_f32 v118, v14, v15
	v_and_b32_e32 v15, 0xffff0000, v17
	v_lshlrev_b32_e32 v14, 16, v17
	v_pk_mul_f32 v[14:15], v[14:15], s[38:39] op_sel_hi:[1,0]
	s_nop 0
	v_cvt_pk_bf16_f32 v119, v14, v15
	v_and_b32_e32 v15, 0xffff0000, v10
	v_lshlrev_b32_e32 v14, 16, v10
	v_pk_mul_f32 v[14:15], v[14:15], s[38:39] op_sel_hi:[1,0]
	s_nop 0
	v_cvt_pk_bf16_f32 v120, v14, v15
	v_and_b32_e32 v15, 0xffff0000, v11
	v_lshlrev_b32_e32 v14, 16, v11
	v_pk_mul_f32 v[10:11], v[14:15], s[38:39] op_sel_hi:[1,0]
	v_mov_b32_e32 v14, v1
	v_cvt_pk_bf16_f32 v121, v10, v11
	v_and_b32_e32 v11, 0xffff0000, v12
	v_lshlrev_b32_e32 v10, 16, v12
	v_pk_mul_f32 v[10:11], v[10:11], s[38:39] op_sel_hi:[1,0]
	v_mov_b32_e32 v15, v1
	v_cvt_pk_bf16_f32 v122, v10, v11
	v_and_b32_e32 v11, 0xffff0000, v13
	v_lshlrev_b32_e32 v10, 16, v13
	v_pk_mul_f32 v[10:11], v[10:11], s[38:39] op_sel_hi:[1,0]
	v_mov_b32_e32 v12, v1
	v_cvt_pk_bf16_f32 v123, v10, v11
	v_and_b32_e32 v11, 0xffff0000, v6
	v_lshlrev_b32_e32 v10, 16, v6
	v_pk_mul_f32 v[10:11], v[10:11], s[38:39] op_sel_hi:[1,0]
	v_mov_b32_e32 v13, v1
	v_cvt_pk_bf16_f32 v124, v10, v11
	v_and_b32_e32 v11, 0xffff0000, v7
	v_lshlrev_b32_e32 v10, 16, v7
	v_pk_mul_f32 v[6:7], v[10:11], s[38:39] op_sel_hi:[1,0]
	v_mov_b32_e32 v10, v1
	v_cvt_pk_bf16_f32 v125, v6, v7
	v_and_b32_e32 v7, 0xffff0000, v8
	v_lshlrev_b32_e32 v6, 16, v8
	v_pk_mul_f32 v[6:7], v[6:7], s[38:39] op_sel_hi:[1,0]
	v_mov_b32_e32 v8, v1
	v_cvt_pk_bf16_f32 v126, v6, v7
	v_and_b32_e32 v7, 0xffff0000, v9
	v_lshlrev_b32_e32 v6, 16, v9
	v_pk_mul_f32 v[6:7], v[6:7], s[38:39] op_sel_hi:[1,0]
	v_mov_b32_e32 v9, v1
	v_cvt_pk_bf16_f32 v127, v6, v7
	v_and_b32_e32 v7, 0xffff0000, v2
	v_lshlrev_b32_e32 v6, 16, v2
	v_pk_mul_f32 v[6:7], v[6:7], s[38:39] op_sel_hi:[1,0]
	v_mov_b32_e32 v11, v1
	v_cvt_pk_bf16_f32 v128, v6, v7
	v_and_b32_e32 v7, 0xffff0000, v3
	v_lshlrev_b32_e32 v6, 16, v3
	v_pk_mul_f32 v[2:3], v[6:7], s[38:39] op_sel_hi:[1,0]
	v_mov_b32_e32 v6, v1
	v_cvt_pk_bf16_f32 v129, v2, v3
	v_and_b32_e32 v3, 0xffff0000, v4
	v_lshlrev_b32_e32 v2, 16, v4
	v_pk_mul_f32 v[2:3], v[2:3], s[38:39] op_sel_hi:[1,0]
	v_mov_b32_e32 v4, v1
	v_cvt_pk_bf16_f32 v130, v2, v3
	v_and_b32_e32 v3, 0xffff0000, v5
	v_lshlrev_b32_e32 v2, 16, v5
	v_pk_mul_f32 v[2:3], v[2:3], s[38:39] op_sel_hi:[1,0]
	v_mov_b32_e32 v5, v1
	v_cvt_pk_bf16_f32 v131, v2, v3
	v_mov_b32_e32 v2, v1
	v_mov_b32_e32 v3, v1
	v_mov_b32_e32 v7, v1
	v_mov_b64_e32 v[46:47], v[14:15]
	v_mov_b64_e32 v[30:31], v[14:15]
	v_mov_b64_e32 v[62:63], v[14:15]
	v_mov_b64_e32 v[44:45], v[12:13]
	v_mov_b64_e32 v[42:43], v[10:11]
	v_mov_b64_e32 v[40:41], v[8:9]
	v_mov_b64_e32 v[38:39], v[6:7]
	v_mov_b64_e32 v[36:37], v[4:5]
	v_mov_b64_e32 v[34:35], v[2:3]
	v_mov_b64_e32 v[32:33], v[0:1]
	v_mov_b64_e32 v[28:29], v[12:13]
	v_mov_b64_e32 v[26:27], v[10:11]
	v_mov_b64_e32 v[24:25], v[8:9]
	v_mov_b64_e32 v[22:23], v[6:7]
	v_mov_b64_e32 v[20:21], v[4:5]
	v_mov_b64_e32 v[18:19], v[2:3]
	v_mov_b64_e32 v[16:17], v[0:1]
	v_mov_b64_e32 v[60:61], v[12:13]
	v_mov_b64_e32 v[58:59], v[10:11]
	v_mov_b64_e32 v[56:57], v[8:9]
	v_mov_b64_e32 v[54:55], v[6:7]
	v_mov_b64_e32 v[52:53], v[4:5]
	v_mov_b64_e32 v[50:51], v[2:3]
	v_mov_b64_e32 v[48:49], v[0:1]
	s_branch .LBB0_1077

; DI void mla_unit(const Params& p, char* lds, int seqbase, int S, int h, int qb) {
;     ...
;   for (int kt = 0; kt < nkt; ++kt) {
;     if (kt + 2 < nkt) MLA_GLOAD(kt + 2);
;     const u16* kl = Kl + cur * 64 * KP + r32 * KP + 8 * hi;
;     f32x16 p0, p1;
;     { const bf16x8 k0 = *(const bf16x8*)(kl), k1 = *(const bf16x8*)(kl + 32 * KP);
;       p0 = MFMA32(k0, qf[0], negm); p1 = MFMA32(k1, qf[0], negm); }
; #pragma unroll
;     for (int d0 = 1; d0 < 6; ++d0) {
;       const bf16x8 k0 = *(const bf16x8*)(kl + d0 * 16), k1 = *(const bf16x8*)(kl + 32 * KP + d0 * 16);
;       p0 = MFMA32(k0, qf[d0], p0); p1 = MFMA32(k1, qf[d0], p1);
;     }
;     const unsigned tb = trb + cur * (64 * VP * 2);
;     constexpr int R8 = 8 * VP * 2;
;     const s16x4 a0 = tr_read_o<0>(tb), b0 = tr_read_o<R8>(tb), a1 = tr_read_o<2 * R8>(tb), b1 = tr_read_o<3 * R8>(tb);
;     const s16x4 a2 = tr_read_o<4 * R8>(tb), b2 = tr_read_o<5 * R8>(tb), a3 = tr_read_o<6 * R8>(tb), b3 = tr_read_o<7 * R8>(tb);
;     const s16x4 c0 = tr_read_o<64>(tb), d0_ = tr_read_o<R8 + 64>(tb), c1 = tr_read_o<2 * R8 + 64>(tb), d1 = tr_read_o<3 * R8 + 64>(tb);
;     const s16x4 c2 = tr_read_o<4 * R8 + 64>(tb), d2 = tr_read_o<5 * R8 + 64>(tb), c3 = tr_read_o<6 * R8 + 64>(tb), d3 = tr_read_o<7 * R8 + 64>(tb);
;     float pmax = max_nn(p0[0], p1[0]);
; #pragma unroll
;     for (int r = 1; r < 16; ++r) pmax = max_nn(pmax, max_nn(p0[r], p1[r]));
;     pmax = pl32_max(pmax);
;     if (kt == 0 || __any(pmax > 8.f)) {
;       const float delta = kt == 0 ? pmax : fmaxf(pmax, 0.f);
;       const float alpha = kt == 0 ? 1.f : __builtin_amdgcn_exp2f(-delta);
; #pragma unroll
;       for (int r = 0; r < 16; ++r) { negm[r] -= delta; p0[r] -= delta; p1[r] -= delta; o0[r] *= alpha; o1[r] *= alpha; }
;       l_run *= alpha;
;     }
;     float ps = 0.f;
; #pragma unroll
;     for (int r = 0; r < 16; ++r) { p0[r] = __builtin_amdgcn_exp2f(p0[r]); p1[r] = __builtin_amdgcn_exp2f(p1[r]); ps += p0[r] + p1[r]; }
;     ps = pl32_sum(ps);
;     l_run += ps;
;     const bf16x8 pb0 = pack8(p0, 0), pb1 = pack8(p0, 1), pb2 = pack8(p1, 0), pb3 = pack8(p1, 1);
;     LGKM0();
;     o0 = MFMA32(cat4(a0, b0), pb0, o0); o1 = MFMA32(cat4(c0, d0_), pb0, o1);
;     o0 = MFMA32(cat4(a1, b1), pb1, o0); o1 = MFMA32(cat4(c1, d1), pb1, o1);
;     o0 = MFMA32(cat4(a2, b2), pb2, o0); o1 = MFMA32(cat4(c2, d2), pb2, o1);
.LBB0_1076:
	s_add_i32 s28, s36, 1
	s_cmp_lg_u32 s36, 2
	s_cselect_b32 s36, s28, 0
	s_add_i32 s28, s63, 1
	s_cmp_lg_u32 s63, 2
	s_cselect_b32 s63, s28, 0
	s_add_i32 s64, s64, 1
	s_add_u32 s46, s46, 0x42000
	s_addc_u32 s47, s47, 0
	v_add_f32_e32 v153, v153, v0
	s_cmp_lg_u32 s46, 0x2100000
	s_cbranch_scc0 .LBB0_1063
.LBB0_1077:
	s_cmpk_lt_u32 s64, 0x7e
	s_cselect_b64 s[48:49], -1, 0
.LBB0_1081:
	s_mul_i32 s28, s36, 0x3400
	v_add_u32_e32 v0, s28, v181
	ds_read_b128 v[2:5], v0
	ds_read_b128 v[6:9], v0 offset:32
	s_mul_i32 s28, s36, 0x3000
	s_cmp_eq_u32 s46, 0
	s_cselect_b64 s[50:51], -1, 0
	s_waitcnt lgkmcnt(1)
	v_mfma_f32_32x32x16_bf16 v[64:79], v[2:5], v[116:119], v[48:63]
	ds_read_b128 v[2:5], v0 offset:6656
	ds_read_b128 v[10:13], v0 offset:6688
	s_cmp_lg_u32 s46, 0
	s_waitcnt lgkmcnt(1)
	v_mfma_f32_32x32x16_bf16 v[80:95], v[2:5], v[116:119], v[48:63]
	v_mfma_f32_32x32x16_bf16 v[64:79], v[6:9], v[120:123], v[64:79]
	ds_read_b128 v[2:5], v0 offset:64
	ds_read_b128 v[6:9], v0 offset:96
	s_waitcnt lgkmcnt(2)
	v_mfma_f32_32x32x16_bf16 v[80:95], v[10:13], v[120:123], v[80:95]
	s_waitcnt lgkmcnt(1)
	v_mfma_f32_32x32x16_bf16 v[64:79], v[2:5], v[124:127], v[64:79]
	ds_read_b128 v[2:5], v0 offset:6720
	ds_read_b128 v[10:13], v0 offset:6752
	s_waitcnt lgkmcnt(1)
	v_mfma_f32_32x32x16_bf16 v[80:95], v[2:5], v[124:127], v[80:95]
	ds_read_b128 v[2:5], v0 offset:128
	ds_read_b128 v[186:189], v0 offset:160
	v_mfma_f32_32x32x16_bf16 v[64:79], v[6:9], v[128:131], v[64:79]
	s_waitcnt lgkmcnt(2)
	v_mfma_f32_32x32x16_bf16 v[80:95], v[10:13], v[128:131], v[80:95]
	s_waitcnt lgkmcnt(1)
	v_mfma_f32_32x32x16_bf16 v[64:79], v[2:5], v[112:115], v[64:79]
	ds_read_b128 v[2:5], v0 offset:6784
	ds_read_b128 v[132:135], v0 offset:6816
	v_add_u32_e32 v0, s28, v182
	ds_read_b64_tr_b16 v[144:145], v0 offset:0
	ds_read_b64_tr_b16 v[146:147], v0 offset:0x600
	ds_read_b64_tr_b16 v[136:137], v0 offset:0xc00
	ds_read_b64_tr_b16 v[138:139], v0 offset:0x1200
	ds_read_b64_tr_b16 v[10:11], v0 offset:0x1800
	s_waitcnt lgkmcnt(1)
	v_mfma_f32_32x32x16_bf16 v[80:95], v[2:5], v[112:115], v[80:95]
	ds_read_b64_tr_b16 v[12:13], v0 offset:0x1e00
	ds_read_b64_tr_b16 v[6:7], v0 offset:0x2400
	ds_read_b64_tr_b16 v[8:9], v0 offset:0x2a00
	ds_read_b64_tr_b16 v[148:149], v0 offset:64
	ds_read_b64_tr_b16 v[150:151], v0 offset:0x640
	ds_read_b64_tr_b16 v[140:141], v0 offset:0xc40
	ds_read_b64_tr_b16 v[142:143], v0 offset:0x1240
	s_waitcnt lgkmcnt(0)
	v_mfma_f32_32x32x16_bf16 v[80:95], v[132:135], v[108:111], v[80:95]
	ds_read_b64_tr_b16 v[132:133], v0 offset:0x1840
	ds_read_b64_tr_b16 v[134:135], v0 offset:0x1e40
	ds_read_b64_tr_b16 v[2:3], v0 offset:0x2440
	ds_read_b64_tr_b16 v[4:5], v0 offset:0x2a40
	v_mfma_f32_32x32x16_bf16 v[64:79], v[186:189], v[108:111], v[64:79]
	s_nop 10
	v_max3_f32 v0, v80, v81, v82
	v_max3_f32 v14, v64, v65, v66
	v_max3_f32 v0, v0, v83, v84
	v_max3_f32 v14, v14, v67, v68
	v_max3_f32 v0, v0, v85, v86
	v_max3_f32 v14, v14, v69, v70
	v_max3_f32 v0, v0, v87, v88
	v_max3_f32 v14, v14, v71, v72
	v_max3_f32 v0, v0, v89, v90
	v_max3_f32 v14, v14, v73, v74
	v_max3_f32 v0, v0, v91, v92
	v_max3_f32 v14, v14, v75, v76
	v_max3_f32 v0, v0, v93, v94
	v_max3_f32 v14, v14, v77, v78
	v_max3_f32 v0, v0, v95, v79
	v_max_f32_e32 v0, v0, v14
	v_mov_b32_e32 v14, v0
	s_nop 1
	v_permlane32_swap_b32_e32 v0, v14
	v_max_f32_e32 v14, v0, v14
	s_cbranch_scc0 .LBB0_1091
	v_cmp_lt_f32_e32 vcc, s60, v14
	s_mov_b64 s[54:55], 0
	s_mov_b64 s[52:53], 0
	s_cbranch_vccnz .Lmla_rare_0
.LBB0_1088:
	v_exp_f32_e32 v15, v64
	v_exp_f32_e32 v80, v80
	v_exp_f32_e32 v64, v65
	v_exp_f32_e32 v81, v81
	v_exp_f32_e32 v65, v66
	v_exp_f32_e32 v82, v82
	v_exp_f32_e32 v66, v67
	v_exp_f32_e32 v83, v83
	v_add_f32_e32 v0, v80, v15
	v_exp_f32_e32 v67, v68
	v_exp_f32_e32 v84, v84
	v_add_f32_e32 v14, v81, v64
	v_exp_f32_e32 v68, v69
	v_exp_f32_e32 v85, v85
	v_add_f32_e32 v0, v14, v0
	v_add_f32_e32 v14, v82, v65
	v_exp_f32_e32 v69, v70
	v_exp_f32_e32 v86, v86
	v_add_f32_e32 v0, v14, v0
	v_add_f32_e32 v14, v83, v66
	v_exp_f32_e32 v70, v71
	v_exp_f32_e32 v87, v87
	v_add_f32_e32 v0, v14, v0
	v_add_f32_e32 v14, v84, v67
	v_exp_f32_e32 v71, v72
	v_exp_f32_e32 v88, v88
	v_add_f32_e32 v0, v14, v0
	v_add_f32_e32 v14, v85, v68
	v_exp_f32_e32 v72, v73
	v_exp_f32_e32 v89, v89
	v_add_f32_e32 v0, v14, v0
	v_add_f32_e32 v14, v86, v69
	v_exp_f32_e32 v73, v74
	v_exp_f32_e32 v90, v90
	v_add_f32_e32 v0, v14, v0
	v_add_f32_e32 v14, v87, v70
	v_exp_f32_e32 v74, v75
	v_exp_f32_e32 v91, v91
	v_add_f32_e32 v0, v14, v0
	v_add_f32_e32 v14, v88, v71
	v_exp_f32_e32 v75, v76
	v_exp_f32_e32 v92, v92
	v_add_f32_e32 v0, v14, v0
	v_add_f32_e32 v14, v89, v72
	v_exp_f32_e32 v76, v77
	v_exp_f32_e32 v93, v93
	v_add_f32_e32 v0, v14, v0
	v_add_f32_e32 v14, v90, v73
	v_exp_f32_e32 v77, v78
	v_exp_f32_e32 v94, v94
	v_add_f32_e32 v0, v14, v0
	v_add_f32_e32 v14, v91, v74
	v_exp_f32_e32 v78, v79
	v_exp_f32_e32 v79, v95
	v_add_f32_e32 v0, v14, v0
	v_add_f32_e32 v14, v92, v75
	v_add_f32_e32 v0, v14, v0
	v_add_f32_e32 v14, v93, v76
	v_add_f32_e32 v0, v14, v0
	v_add_f32_e32 v14, v94, v77
	v_add_f32_e32 v0, v14, v0
	v_add_f32_e32 v14, v79, v78
	v_add_f32_e32 v0, v14, v0
	s_waitcnt lgkmcnt(0)
	v_cvt_pk_bf16_f32 v64, v15, v64
	v_cvt_pk_bf16_f32 v65, v65, v66
	v_cvt_pk_bf16_f32 v66, v67, v68
	v_cvt_pk_bf16_f32 v67, v69, v70
	v_cvt_pk_bf16_f32 v68, v71, v72
	v_cvt_pk_bf16_f32 v69, v73, v74
	v_cvt_pk_bf16_f32 v70, v75, v76
	v_cvt_pk_bf16_f32 v71, v77, v78
	v_cvt_pk_bf16_f32 v72, v80, v81
	v_cvt_pk_bf16_f32 v73, v82, v83
	v_cvt_pk_bf16_f32 v74, v84, v85
	v_cvt_pk_bf16_f32 v75, v86, v87
	v_cvt_pk_bf16_f32 v76, v88, v89
	v_cvt_pk_bf16_f32 v77, v90, v91
	v_cvt_pk_bf16_f32 v78, v92, v93
	v_cvt_pk_bf16_f32 v79, v94, v79
	v_mfma_f32_32x32x16_bf16 v[32:47], v[144:147], v[64:67], v[32:47]
	s_andn2_b64 vcc, exec, s[48:49]
	s_waitcnt vmcnt(0)
	s_barrier
	v_mfma_f32_32x32x16_bf16 v[16:31], v[148:151], v[64:67], v[16:31]
	v_mfma_f32_32x32x16_bf16 v[32:47], v[136:139], v[68:71], v[32:47]
	v_mfma_f32_32x32x16_bf16 v[16:31], v[140:143], v[68:71], v[16:31]
	v_mfma_f32_32x32x16_bf16 v[32:47], v[10:13], v[72:75], v[32:47]
	v_mfma_f32_32x32x16_bf16 v[16:31], v[132:135], v[72:75], v[16:31]
	v_mfma_f32_32x32x16_bf16 v[32:47], v[6:9], v[76:79], v[32:47]
	v_mfma_f32_32x32x16_bf16 v[16:31], v[2:5], v[76:79], v[16:31]
	s_cbranch_vccnz .LBB0_1076
	s_mul_i32 s50, s63, 0x3400
	s_mul_i32 s28, s63, 0x3000
	s_add_u32 s28, s28, 0x9c00
	s_lshl_b32 s101, s100, 10
	s_add_u32 m0, s50, s101
	s_nop 0
	global_load_lds_dwordx4 v200, s[24:25]
	v_add_u32_e32 v200, v200, v201
	s_cmp_lt_u32 s100, 5
	s_cbranch_scc0 .Lmd_skb3
	s_add_u32 m0, m0, 0x2000
	s_nop 0
	global_load_lds_dwordx4 v202, s[24:25]
	v_add_u32_e32 v202, v202, v203
.Lmd_skb3:
	s_add_u32 m0, s28, s101
	s_nop 0
	global_load_lds_dwordx4 v204, s[24:25]
	v_add_u32_e32 v204, 0x42000, v204
	s_cmp_lt_u32 s100, 4
	s_cbranch_scc0 .Lmd_svb3
	s_add_u32 m0, m0, 0x2000
	s_nop 0
	global_load_lds_dwordx4 v205, s[24:25]
	v_add_u32_e32 v205, 0x42000, v205
.Lmd_svb3:
	s_branch .LBB0_1076

; DI float bfs2f(short v) { return __uint_as_float(((unsigned)(u16)v) << 16); }
; DI u16 f2bf(float a) { return (u16)(pk2(a, 0.f) & 0xffffu); }
; #define MLA_GLOAD(T) do { rkn = *(const u32x4*)(kvsrc + (size_t)(T) * 64 * KVP); rvv = *(const u32x4*)(kvsrc + (size_t)(T) * 64 * KVP + 64); \
;     if (kr_on) rkr = *(const u32x4*)(krsrc + (size_t)(T) * 64 * 32); } while (0)
; #define MLA_LSTORE(B) do { u16* kd = Kl + (B) * 64 * KP; u16* vd = Vl + (B) * 64 * VP; *(u32x4*)(kd + kdst0) = rkn; *(u32x4*)(vd + vdst) = rvv; \
;     if (kr_on) *(u32x4*)(kd + kdst2) = rkr; } while (0)
; DI void mla_unit(const Params& p, char* lds, int seqbase, int S, int h, int qb) {
;     ...
;   const int pos = qb * 256 + wid * 32 + r32, qrow = seqbase + pos;
;   bf16x8 qf[6];
; #pragma unroll
;   for (int d0 = 0; d0 < 6; ++d0) qf[d0] = *(const bf16x8*)(Q + (size_t)qrow * 1536 + h * 96 + d0 * 16 + 8 * hi);
;   const float C = 0.10206207261596577f * LOG2E;
; #pragma unroll
;   for (int j = 0; j < 8; ++j) {
;     const float c = ct[pos * 16 + 8 * hi + j], s = st[pos * 16 + 8 * hi + j];
;     const float t1 = bfs2f(qf[4][j]), t2 = bfs2f(qf[5][j]);
;     qf[4][j] = (short)f2bf((t1 * c - t2 * s) * C); qf[5][j] = (short)f2bf((t1 * s + t2 * c) * C);
;   }
; #pragma unroll
;   for (int d0 = 0; d0 < 4; ++d0)
; #pragma unroll
;     for (int j = 0; j < 8; ++j) qf[d0][j] = (short)f2bf(bfs2f(qf[d0][j]) * C);
;   const int srow = tid >> 3, sc = tid & 7, rrow = (tid >> 2) & 63, rc = tid & 3;
;   const bool kr_on = tid < 256;
;   const u16* kvsrc = KV + (size_t)(seqbase + srow) * KVP + h * 128 + sc * 8;
;   const u16* krsrc = KR + (size_t)(seqbase + rrow) * 32 + rc * 8;
;   const int kdst0 = srow * KP + sc * 8, kdst2 = rrow * KP + 64 + rc * 8, vdst = srow * VP + sc * 8;
;   float l_run = 0.f; f32x16 o0 = {}, o1 = {}, negm = {};
;   const int nkt = S >> 6;
;   u32x4 rkn, rkr, rvv;
;     ...
;   MLA_GLOAD(0); MLA_LSTORE(0);
;   MLA_GLOAD(1); MLA_LSTORE(1);
.LBB0_1094:
	s_min_i32 s18, s35, 0x7f
	s_lshr_b32 s28, s18, 1
	s_lshl_b32 s40, s18, 7
	s_lshl_b32 s18, s18, 8
	s_and_b32 s41, s40, 0xfffff000
	s_and_b32 s18, s18, 0xf00
	s_and_b32 s28, s28, 8
	s_add_i32 s38, s41, 0x8000
	v_add_u32_e32 v1, s18, v175
	s_or_b32 s55, s28, s3
	v_add_u32_e32 v168, s38, v1
	v_mad_i64_i32 v[4:5], s[28:29], v168, s53, v[164:165]
	s_mul_i32 s18, s55, 0xc0
	v_lshl_add_u64 v[4:5], v[4:5], 0, s[18:19]
	v_lshl_add_u64 v[20:21], v[4:5], 0, v[160:161]
	v_lshl_or_b32 v1, v1, 6, v185
	global_load_dwordx4 v[16:19], v[20:21], off
	global_load_dwordx4 v[12:15], v[20:21], off offset:32
	global_load_dwordx4 v[8:11], v[20:21], off offset:64
	global_load_dwordx4 v[4:7], v[20:21], off offset:96
	global_load_dwordx4 v[32:35], v[20:21], off offset:128
	global_load_dwordx4 v[28:31], v[20:21], off offset:160
	s_nop 0
	global_load_dwordx4 v[20:23], v1, s[10:11] offset:16
	global_load_dwordx4 v[36:39], v1, s[10:11]
	global_load_dwordx4 v[24:27], v1, s[14:15] offset:16
	global_load_dwordx4 v[40:43], v1, s[14:15]
	v_or_b32_e32 v1, s38, v176
	v_mad_i64_i32 v[44:45], s[28:29], v1, s54, v[166:167]
	s_lshl_b32 s18, s55, 8
	v_lshl_add_u64 v[44:45], v[44:45], 0, s[18:19]
	v_lshl_add_u64 v[54:55], v[44:45], 0, v[162:163]
	v_or_b32_e32 v52, s38, v177
	v_ashrrev_i32_e32 v53, 31, v52
	v_lshlrev_b64 v[52:53], 6, v[52:53]
	v_lshl_add_u64 v[52:53], v[154:155], 0, v[52:53]
	s_nop 1
	v_readfirstlane_b32 s96, v54
	v_readfirstlane_b32 s98, v52
	v_readfirstlane_b32 s100, v174
	s_lshr_b32 s100, s100, 6
	s_sub_u32 s96, s96, s24
	s_mul_i32 s101, s100, 0x8400
	s_sub_u32 s96, s96, s101
	s_sub_u32 s98, s98, s24
	s_lshl_b32 s101, s100, 4
	s_and_b32 s101, s101, 63
	s_lshl_b32 s101, s101, 6
	s_sub_u32 s98, s98, s101
	v_and_b32_e32 v206, 63, v174
	v_lshl_add_u32 v206, s100, 6, v206
	v_add_u32_e32 v207, 0x200, v206
	v_mul_u32_u24_e32 v208, 0x13b2, v206
	v_lshrrev_b32_e32 v208, 16, v208
	v_mul_u32_u24_e32 v209, 13, v208
	v_sub_u32_e32 v209, v206, v209
	v_mul_u32_u24_e32 v210, 0x1080, v208
	v_add_u32_e32 v210, s96, v210
	v_lshlrev_b32_e32 v211, 4, v209
	v_cmp_gt_u32_e32 vcc, 8, v209
	s_nop 1
	v_cndmask_b32_e32 v211, 0, v211, vcc
	v_add_u32_e32 v200, v210, v211
	v_lshlrev_b32_e32 v210, 6, v208
	v_add_u32_e32 v210, s98, v210
	v_add_u32_e32 v211, -8, v209
	v_lshl_add_u32 v210, v211, 4, v210
	v_cmp_gt_u32_e32 vcc, 4, v211
	s_nop 1
	v_cndmask_b32_e32 v200, v200, v210, vcc
	v_mov_b32_e32 v211, 0x1000
	v_mov_b32_e32 v201, 0x42000
	v_cndmask_b32_e32 v201, v201, v211, vcc
	v_mul_u32_u24_e32 v208, 0x13b2, v207
	v_lshrrev_b32_e32 v208, 16, v208
	v_mul_u32_u24_e32 v209, 13, v208
	v_sub_u32_e32 v209, v207, v209
	v_mul_u32_u24_e32 v210, 0x1080, v208
	v_add_u32_e32 v210, s96, v210
	v_lshlrev_b32_e32 v211, 4, v209
	v_cmp_gt_u32_e32 vcc, 8, v209
	s_nop 1
	v_cndmask_b32_e32 v211, 0, v211, vcc
	v_add_u32_e32 v202, v210, v211
	v_lshlrev_b32_e32 v210, 6, v208
	v_add_u32_e32 v210, s98, v210
	v_add_u32_e32 v211, -8, v209
	v_lshl_add_u32 v210, v211, 4, v210
	v_cmp_gt_u32_e32 vcc, 4, v211
	s_nop 1
	v_cndmask_b32_e32 v202, v202, v210, vcc
	v_mov_b32_e32 v211, 0x1000
	v_mov_b32_e32 v203, 0x42000
	v_cndmask_b32_e32 v203, v203, v211, vcc
	v_mul_u32_u24_e32 v208, 0x1556, v206
	v_lshrrev_b32_e32 v208, 16, v208
	v_mul_u32_u24_e32 v209, 12, v208
	v_sub_u32_e32 v209, v206, v209
	v_min_u32_e32 v209, 7, v209
	v_mul_u32_u24_e32 v210, 0x1080, v208
	v_add_u32_e32 v210, s96, v210
	v_lshl_add_u32 v210, v209, 4, v210
	v_add_u32_e32 v204, 0x80, v210
	v_mul_u32_u24_e32 v208, 0x1556, v207
	v_lshrrev_b32_e32 v208, 16, v208
	v_mul_u32_u24_e32 v209, 12, v208
	v_sub_u32_e32 v209, v207, v209
	v_min_u32_e32 v209, 7, v209
	v_mul_u32_u24_e32 v210, 0x1080, v208
	v_add_u32_e32 v210, s96, v210
	v_lshl_add_u32 v210, v209, 4, v210
	v_add_u32_e32 v205, 0x80, v210
	s_mov_b32 s96, 0
	s_mov_b32 s98, 0x9c00
	s_lshl_b32 s101, s100, 10
	s_add_u32 m0, s96, s101
	s_nop 0
	global_load_lds_dwordx4 v200, s[24:25]
	v_add_u32_e32 v200, v200, v201
	s_cmp_lt_u32 s100, 5
	s_cbranch_scc0 .Lmd_skb1
	s_add_u32 m0, m0, 0x2000
	s_nop 0
	global_load_lds_dwordx4 v202, s[24:25]
	v_add_u32_e32 v202, v202, v203

; DI float bfs2f(short v) { return __uint_as_float(((unsigned)(u16)v) << 16); }
; DI u16 f2bf(float a) { return (u16)(pk2(a, 0.f) & 0xffffu); }
; #define MLA_GLOAD(T) do { rkn = *(const u32x4*)(kvsrc + (size_t)(T) * 64 * KVP); rvv = *(const u32x4*)(kvsrc + (size_t)(T) * 64 * KVP + 64); \
;     if (kr_on) rkr = *(const u32x4*)(krsrc + (size_t)(T) * 64 * 32); } while (0)
; #define MLA_LSTORE(B) do { u16* kd = Kl + (B) * 64 * KP; u16* vd = Vl + (B) * 64 * VP; *(u32x4*)(kd + kdst0) = rkn; *(u32x4*)(vd + vdst) = rvv; \
;     if (kr_on) *(u32x4*)(kd + kdst2) = rkr; } while (0)
; DI void mla_unit(const Params& p, char* lds, int seqbase, int S, int h, int qb) {
;     ...
;   const float C = 0.10206207261596577f * LOG2E;
; #pragma unroll
;   for (int j = 0; j < 8; ++j) {
;     const float c = ct[pos * 16 + 8 * hi + j], s = st[pos * 16 + 8 * hi + j];
;     const float t1 = bfs2f(qf[4][j]), t2 = bfs2f(qf[5][j]);
;     qf[4][j] = (short)f2bf((t1 * c - t2 * s) * C); qf[5][j] = (short)f2bf((t1 * s + t2 * c) * C);
;   }
; #pragma unroll
;   for (int d0 = 0; d0 < 4; ++d0)
; #pragma unroll
;     for (int j = 0; j < 8; ++j) qf[d0][j] = (short)f2bf(bfs2f(qf[d0][j]) * C);
;   const int srow = tid >> 3, sc = tid & 7, rrow = (tid >> 2) & 63, rc = tid & 3;
;   const bool kr_on = tid < 256;
;   const u16* kvsrc = KV + (size_t)(seqbase + srow) * KVP + h * 128 + sc * 8;
;   const u16* krsrc = KR + (size_t)(seqbase + rrow) * 32 + rc * 8;
;   const int kdst0 = srow * KP + sc * 8, kdst2 = rrow * KP + 64 + rc * 8, vdst = srow * VP + sc * 8;
;   float l_run = 0.f; f32x16 o0 = {}, o1 = {}, negm = {};
;   const int nkt = S >> 6;
;   u32x4 rkn, rkr, rvv;
;     ...
;   MLA_GLOAD(0); MLA_LSTORE(0);
;   MLA_GLOAD(1); MLA_LSTORE(1);
;   __syncthreads();
;   int cur = 0, nx2 = 2;
;   if (wid >= 4) __builtin_amdgcn_s_setprio(1);
.Lmd_svb2:
	s_waitcnt vmcnt(0)
	s_waitcnt lgkmcnt(0)
	s_barrier
	s_and_saveexec_b64 s[38:39], s[4:5]
	s_setprio 1
	s_or_b64 exec, exec, s[38:39]
	v_add_u32_e32 v44, s41, v186
	s_and_b32 s18, s40, 0x800
	v_ashrrev_i32_e32 v45, 31, v44
	s_or_b32 s18, s18, s57
	v_lshlrev_b64 v[44:45], 6, v[44:45]
	v_add_u32_e32 v1, s41, v187
	v_mov_b32_e32 v2, s18
	v_lshl_add_u64 v[170:171], v[156:157], 0, v[44:45]
	v_mad_i64_i32 v[44:45], s[28:29], v1, s54, v[2:3]
	v_and_b32_e32 v47, 0xffff0000, v28
	v_lshlrev_b32_e32 v46, 16, v28
	v_lshl_add_u64 v[172:173], v[158:159], 0, v[44:45]
	v_and_b32_e32 v45, 0xffff0000, v32
	v_lshlrev_b32_e32 v44, 16, v32
	v_pk_mul_f32 v[48:49], v[36:37], v[46:47]
	v_lshlrev_b32_e32 v32, 16, v29
	v_pk_fma_f32 v[48:49], v[40:41], v[44:45], v[48:49]
	v_pk_mul_f32 v[40:41], v[40:41], v[46:47]
	v_pk_mul_f32 v[48:49], v[48:49], s[20:21] op_sel_hi:[1,0]
	v_pk_fma_f32 v[36:37], v[36:37], v[44:45], v[40:41] neg_lo:[0,0,1] neg_hi:[0,0,1]
	v_cvt_pk_bf16_f32 v110, v48, v49
	v_pk_mul_f32 v[36:37], v[36:37], s[20:21] op_sel_hi:[1,0]
	v_mov_b32_e32 v2, v3
	v_cvt_pk_bf16_f32 v114, v36, v37
	v_and_b32_e32 v37, 0xffff0000, v33
	v_lshlrev_b32_e32 v36, 16, v33
	v_and_b32_e32 v33, 0xffff0000, v29
	v_pk_mul_f32 v[28:29], v[42:43], v[36:37]
	v_ashrrev_i32_e32 v169, 31, v168
	v_pk_fma_f32 v[28:29], v[38:39], v[32:33], v[28:29]
	s_mov_b32 s18, 0
	v_pk_mul_f32 v[28:29], v[28:29], s[20:21] op_sel_hi:[1,0]
	s_mov_b32 s58, 2
	v_cvt_pk_bf16_f32 v111, v28, v29
	v_pk_mul_f32 v[28:29], v[42:43], v[32:33]
	v_and_b32_e32 v33, 0xffff0000, v30
	v_pk_fma_f32 v[28:29], v[38:39], v[36:37], v[28:29] neg_lo:[0,0,1] neg_hi:[0,0,1]
	v_lshlrev_b32_e32 v32, 16, v30
	v_pk_mul_f32 v[28:29], v[28:29], s[20:21] op_sel_hi:[1,0]
	v_mov_b32_e32 v1, 0
	v_cvt_pk_bf16_f32 v115, v28, v29
	v_and_b32_e32 v29, 0xffff0000, v34
	v_lshlrev_b32_e32 v28, 16, v34
	v_pk_mul_f32 v[36:37], v[24:25], v[28:29]
	v_pk_mul_f32 v[24:25], v[24:25], v[32:33]
	v_pk_fma_f32 v[36:37], v[20:21], v[32:33], v[36:37]
	v_pk_fma_f32 v[20:21], v[20:21], v[28:29], v[24:25] neg_lo:[0,0,1] neg_hi:[0,0,1]
	v_and_b32_e32 v25, 0xffff0000, v31
	v_pk_mul_f32 v[20:21], v[20:21], s[20:21] op_sel_hi:[1,0]
	v_lshlrev_b32_e32 v24, 16, v31
	v_cvt_pk_bf16_f32 v116, v20, v21
	v_and_b32_e32 v21, 0xffff0000, v35
	v_lshlrev_b32_e32 v20, 16, v35
	v_pk_mul_f32 v[28:29], v[26:27], v[20:21]
	v_pk_mul_f32 v[36:37], v[36:37], s[20:21] op_sel_hi:[1,0]
	v_pk_fma_f32 v[28:29], v[22:23], v[24:25], v[28:29]
	v_pk_mul_f32 v[24:25], v[26:27], v[24:25]
	v_pk_mul_f32 v[28:29], v[28:29], s[20:21] op_sel_hi:[1,0]
	v_pk_fma_f32 v[20:21], v[22:23], v[20:21], v[24:25] neg_lo:[0,0,1] neg_hi:[0,0,1]
	v_cvt_pk_bf16_f32 v112, v36, v37
	v_pk_mul_f32 v[20:21], v[20:21], s[20:21] op_sel_hi:[1,0]
	v_cvt_pk_bf16_f32 v113, v28, v29
	v_cvt_pk_bf16_f32 v117, v20, v21
	v_and_b32_e32 v21, 0xffff0000, v16
	v_lshlrev_b32_e32 v20, 16, v16
	v_pk_mul_f32 v[20:21], v[20:21], s[20:21] op_sel_hi:[1,0]
	s_mov_b64 s[38:39], 0
	v_cvt_pk_bf16_f32 v118, v20, v21
	v_and_b32_e32 v21, 0xffff0000, v17
	v_lshlrev_b32_e32 v20, 16, v17
	v_pk_mul_f32 v[16:17], v[20:21], s[20:21] op_sel_hi:[1,0]
	s_mov_b32 s59, 0
	v_cvt_pk_bf16_f32 v119, v16, v17
	v_and_b32_e32 v17, 0xffff0000, v18
	v_lshlrev_b32_e32 v16, 16, v18
	v_pk_mul_f32 v[16:17], v[16:17], s[20:21] op_sel_hi:[1,0]
	s_nop 0
	v_cvt_pk_bf16_f32 v120, v16, v17
	v_and_b32_e32 v17, 0xffff0000, v19
	v_lshlrev_b32_e32 v16, 16, v19
	v_pk_mul_f32 v[16:17], v[16:17], s[20:21] op_sel_hi:[1,0]
	s_nop 0
	v_cvt_pk_bf16_f32 v121, v16, v17
	v_and_b32_e32 v17, 0xffff0000, v12
	v_lshlrev_b32_e32 v16, 16, v12
	v_pk_mul_f32 v[16:17], v[16:17], s[20:21] op_sel_hi:[1,0]
	s_nop 0
	v_cvt_pk_bf16_f32 v122, v16, v17
	v_and_b32_e32 v17, 0xffff0000, v13
	v_lshlrev_b32_e32 v16, 16, v13
	v_pk_mul_f32 v[12:13], v[16:17], s[20:21] op_sel_hi:[1,0]
	v_mov_b32_e32 v16, v3
	v_cvt_pk_bf16_f32 v123, v12, v13
	v_and_b32_e32 v13, 0xffff0000, v14
	v_lshlrev_b32_e32 v12, 16, v14
	v_pk_mul_f32 v[12:13], v[12:13], s[20:21] op_sel_hi:[1,0]
	v_mov_b32_e32 v17, v3
	v_cvt_pk_bf16_f32 v124, v12, v13
	v_and_b32_e32 v13, 0xffff0000, v15
	v_lshlrev_b32_e32 v12, 16, v15
	v_pk_mul_f32 v[12:13], v[12:13], s[20:21] op_sel_hi:[1,0]
	v_mov_b32_e32 v14, v3
	v_cvt_pk_bf16_f32 v125, v12, v13
	v_and_b32_e32 v13, 0xffff0000, v8
	v_lshlrev_b32_e32 v12, 16, v8
	v_pk_mul_f32 v[12:13], v[12:13], s[20:21] op_sel_hi:[1,0]
	v_mov_b32_e32 v15, v3
	v_cvt_pk_bf16_f32 v126, v12, v13
	v_and_b32_e32 v13, 0xffff0000, v9
	v_lshlrev_b32_e32 v12, 16, v9
	v_pk_mul_f32 v[8:9], v[12:13], s[20:21] op_sel_hi:[1,0]
	v_mov_b32_e32 v12, v3
	v_cvt_pk_bf16_f32 v127, v8, v9
	v_and_b32_e32 v9, 0xffff0000, v10
	v_lshlrev_b32_e32 v8, 16, v10
	v_pk_mul_f32 v[8:9], v[8:9], s[20:21] op_sel_hi:[1,0]
	v_mov_b32_e32 v10, v3
	v_cvt_pk_bf16_f32 v128, v8, v9
	v_and_b32_e32 v9, 0xffff0000, v11
	v_lshlrev_b32_e32 v8, 16, v11
	v_pk_mul_f32 v[8:9], v[8:9], s[20:21] op_sel_hi:[1,0]
	v_mov_b32_e32 v11, v3
	v_cvt_pk_bf16_f32 v129, v8, v9
	v_and_b32_e32 v9, 0xffff0000, v4
	v_lshlrev_b32_e32 v8, 16, v4
	v_pk_mul_f32 v[8:9], v[8:9], s[20:21] op_sel_hi:[1,0]
	v_mov_b32_e32 v13, v3
	v_cvt_pk_bf16_f32 v130, v8, v9
	v_and_b32_e32 v9, 0xffff0000, v5
	v_lshlrev_b32_e32 v8, 16, v5
	v_pk_mul_f32 v[4:5], v[8:9], s[20:21] op_sel_hi:[1,0]
	v_mov_b32_e32 v8, v3
	v_cvt_pk_bf16_f32 v131, v4, v5
	v_and_b32_e32 v5, 0xffff0000, v6
	v_lshlrev_b32_e32 v4, 16, v6
	v_pk_mul_f32 v[4:5], v[4:5], s[20:21] op_sel_hi:[1,0]
	v_mov_b32_e32 v6, v3
	v_cvt_pk_bf16_f32 v132, v4, v5
	v_and_b32_e32 v5, 0xffff0000, v7
	v_lshlrev_b32_e32 v4, 16, v7
	v_pk_mul_f32 v[4:5], v[4:5], s[20:21] op_sel_hi:[1,0]
	v_mov_b32_e32 v7, v3
	v_cvt_pk_bf16_f32 v133, v4, v5
	v_mov_b32_e32 v4, v3
	v_mov_b32_e32 v5, v3
	v_mov_b32_e32 v9, v3
	v_mov_b64_e32 v[48:49], v[16:17]
	v_mov_b64_e32 v[32:33], v[16:17]
	v_mov_b64_e32 v[64:65], v[16:17]
	v_mov_b64_e32 v[46:47], v[14:15]
	v_mov_b64_e32 v[44:45], v[12:13]
	v_mov_b64_e32 v[42:43], v[10:11]
	v_mov_b64_e32 v[40:41], v[8:9]
	v_mov_b64_e32 v[38:39], v[6:7]
	v_mov_b64_e32 v[36:37], v[4:5]
	v_mov_b64_e32 v[34:35], v[2:3]
	v_mov_b64_e32 v[30:31], v[14:15]
	v_mov_b64_e32 v[28:29], v[12:13]
	v_mov_b64_e32 v[26:27], v[10:11]
	v_mov_b64_e32 v[24:25], v[8:9]
	v_mov_b64_e32 v[22:23], v[6:7]
	v_mov_b64_e32 v[20:21], v[4:5]
	v_mov_b64_e32 v[18:19], v[2:3]
	v_mov_b64_e32 v[62:63], v[14:15]
	v_mov_b64_e32 v[60:61], v[12:13]
	v_mov_b64_e32 v[58:59], v[10:11]
	v_mov_b64_e32 v[56:57], v[8:9]
	v_mov_b64_e32 v[54:55], v[6:7]
	v_mov_b64_e32 v[52:53], v[4:5]
	v_mov_b64_e32 v[50:51], v[2:3]
	s_branch .LBB0_1107

; DI void mla_unit(const Params& p, char* lds, int seqbase, int S, int h, int qb) {
;     ...
;   for (int kt = 0; kt < nkt; ++kt) {
;     if (kt + 2 < nkt) MLA_GLOAD(kt + 2);
;     const u16* kl = Kl + cur * 64 * KP + r32 * KP + 8 * hi;
;     f32x16 p0, p1;
;     { const bf16x8 k0 = *(const bf16x8*)(kl), k1 = *(const bf16x8*)(kl + 32 * KP);
;       p0 = MFMA32(k0, qf[0], negm); p1 = MFMA32(k1, qf[0], negm); }
; #pragma unroll
;     for (int d0 = 1; d0 < 6; ++d0) {
;       const bf16x8 k0 = *(const bf16x8*)(kl + d0 * 16), k1 = *(const bf16x8*)(kl + 32 * KP + d0 * 16);
;       p0 = MFMA32(k0, qf[d0], p0); p1 = MFMA32(k1, qf[d0], p1);
;     }
;     const unsigned tb = trb + cur * (64 * VP * 2);
;     constexpr int R8 = 8 * VP * 2;
;     const s16x4 a0 = tr_read_o<0>(tb), b0 = tr_read_o<R8>(tb), a1 = tr_read_o<2 * R8>(tb), b1 = tr_read_o<3 * R8>(tb);
;     const s16x4 a2 = tr_read_o<4 * R8>(tb), b2 = tr_read_o<5 * R8>(tb), a3 = tr_read_o<6 * R8>(tb), b3 = tr_read_o<7 * R8>(tb);
;     const s16x4 c0 = tr_read_o<64>(tb), d0_ = tr_read_o<R8 + 64>(tb), c1 = tr_read_o<2 * R8 + 64>(tb), d1 = tr_read_o<3 * R8 + 64>(tb);
;     const s16x4 c2 = tr_read_o<4 * R8 + 64>(tb), d2 = tr_read_o<5 * R8 + 64>(tb), c3 = tr_read_o<6 * R8 + 64>(tb), d3 = tr_read_o<7 * R8 + 64>(tb);
;     float pmax = max_nn(p0[0], p1[0]);
; #pragma unroll
;     for (int r = 1; r < 16; ++r) pmax = max_nn(pmax, max_nn(p0[r], p1[r]));
;     pmax = pl32_max(pmax);
;     if (kt == 0 || __any(pmax > 8.f)) {
;       const float delta = kt == 0 ? pmax : fmaxf(pmax, 0.f);
;       const float alpha = kt == 0 ? 1.f : __builtin_amdgcn_exp2f(-delta);
; #pragma unroll
;       for (int r = 0; r < 16; ++r) { negm[r] -= delta; p0[r] -= delta; p1[r] -= delta; o0[r] *= alpha; o1[r] *= alpha; }
;       l_run *= alpha;
;     }
;     float ps = 0.f;
; #pragma unroll
;     for (int r = 0; r < 16; ++r) { p0[r] = __builtin_amdgcn_exp2f(p0[r]); p1[r] = __builtin_amdgcn_exp2f(p1[r]); ps += p0[r] + p1[r]; }
;     ps = pl32_sum(ps);
;     l_run += ps;
;     const bf16x8 pb0 = pack8(p0, 0), pb1 = pack8(p0, 1), pb2 = pack8(p1, 0), pb3 = pack8(p1, 1);
;     LGKM0();
;     o0 = MFMA32(cat4(a0, b0), pb0, o0); o1 = MFMA32(cat4(c0, d0_), pb0, o1);
;     o0 = MFMA32(cat4(a1, b1), pb1, o0); o1 = MFMA32(cat4(c1, d1), pb1, o1);
;     o0 = MFMA32(cat4(a2, b2), pb2, o0); o1 = MFMA32(cat4(c2, d2), pb2, o1);
.LBB0_1106:
	s_add_i32 s28, s18, 1
	s_cmp_lg_u32 s18, 2
	s_cselect_b32 s18, s28, 0
	s_add_i32 s28, s58, 1
	s_cmp_lg_u32 s58, 2
	s_cselect_b32 s58, s28, 0
	s_add_i32 s59, s59, 1
	s_add_u32 s38, s38, 0x42000
	s_addc_u32 s39, s39, 0
	v_add_f32_e32 v1, v1, v2
	s_cmp_lg_u32 s38, 0x1080000
	s_cbranch_scc0 .LBB0_1093
.LBB0_1107:
	s_cmp_lt_u32 s59, 62
	s_cselect_b64 s[40:41], -1, 0
.LBB0_1111:
	s_mul_i32 s28, s18, 0x3400
	v_add_u32_e32 v2, s28, v181
	ds_read_b128 v[4:7], v2
	ds_read_b128 v[8:11], v2 offset:32
	s_mul_i32 s28, s18, 0x3000
	s_cmp_eq_u32 s38, 0
	s_cselect_b64 s[46:47], -1, 0
	s_waitcnt lgkmcnt(1)
	v_mfma_f32_32x32x16_bf16 v[66:81], v[4:7], v[118:121], v[50:65]
	ds_read_b128 v[4:7], v2 offset:6656
	ds_read_b128 v[12:15], v2 offset:6688
	s_cmp_lg_u32 s38, 0
	s_waitcnt lgkmcnt(1)
	v_mfma_f32_32x32x16_bf16 v[82:97], v[4:7], v[118:121], v[50:65]
	v_mfma_f32_32x32x16_bf16 v[66:81], v[8:11], v[122:125], v[66:81]
	ds_read_b128 v[4:7], v2 offset:64
	ds_read_b128 v[8:11], v2 offset:96
	s_waitcnt lgkmcnt(2)
	v_mfma_f32_32x32x16_bf16 v[82:97], v[12:15], v[122:125], v[82:97]
	s_waitcnt lgkmcnt(1)
	v_mfma_f32_32x32x16_bf16 v[66:81], v[4:7], v[126:129], v[66:81]
	ds_read_b128 v[4:7], v2 offset:6720
	ds_read_b128 v[12:15], v2 offset:6752
	s_waitcnt lgkmcnt(1)
	v_mfma_f32_32x32x16_bf16 v[82:97], v[4:7], v[126:129], v[82:97]
	ds_read_b128 v[4:7], v2 offset:128
	ds_read_b128 v[188:191], v2 offset:160
	v_mfma_f32_32x32x16_bf16 v[66:81], v[8:11], v[130:133], v[66:81]
	s_waitcnt lgkmcnt(2)
	v_mfma_f32_32x32x16_bf16 v[82:97], v[12:15], v[130:133], v[82:97]
	s_waitcnt lgkmcnt(1)
	v_mfma_f32_32x32x16_bf16 v[66:81], v[4:7], v[114:117], v[66:81]
	ds_read_b128 v[4:7], v2 offset:6784
	ds_read_b128 v[134:137], v2 offset:6816
	v_add_u32_e32 v2, s28, v182
	ds_read_b64_tr_b16 v[146:147], v2 offset:0
	ds_read_b64_tr_b16 v[148:149], v2 offset:0x600
	ds_read_b64_tr_b16 v[138:139], v2 offset:0xc00
	ds_read_b64_tr_b16 v[140:141], v2 offset:0x1200
	ds_read_b64_tr_b16 v[12:13], v2 offset:0x1800
	s_waitcnt lgkmcnt(1)
	v_mfma_f32_32x32x16_bf16 v[82:97], v[4:7], v[114:117], v[82:97]
	ds_read_b64_tr_b16 v[14:15], v2 offset:0x1e00
	ds_read_b64_tr_b16 v[8:9], v2 offset:0x2400
	ds_read_b64_tr_b16 v[10:11], v2 offset:0x2a00
	ds_read_b64_tr_b16 v[150:151], v2 offset:64
	ds_read_b64_tr_b16 v[152:153], v2 offset:0x640
	ds_read_b64_tr_b16 v[142:143], v2 offset:0xc40
	ds_read_b64_tr_b16 v[144:145], v2 offset:0x1240
	s_waitcnt lgkmcnt(0)
	v_mfma_f32_32x32x16_bf16 v[82:97], v[134:137], v[110:113], v[82:97]
	ds_read_b64_tr_b16 v[134:135], v2 offset:0x1840
	ds_read_b64_tr_b16 v[136:137], v2 offset:0x1e40
	ds_read_b64_tr_b16 v[4:5], v2 offset:0x2440
	ds_read_b64_tr_b16 v[6:7], v2 offset:0x2a40
	v_mfma_f32_32x32x16_bf16 v[66:81], v[188:191], v[110:113], v[66:81]
	s_nop 10
	v_max3_f32 v2, v82, v83, v84
	v_max3_f32 v16, v66, v67, v68
	v_max3_f32 v2, v2, v85, v86
	v_max3_f32 v16, v16, v69, v70
	v_max3_f32 v2, v2, v87, v88
	v_max3_f32 v16, v16, v71, v72
	v_max3_f32 v2, v2, v89, v90
	v_max3_f32 v16, v16, v73, v74
	v_max3_f32 v2, v2, v91, v92
	v_max3_f32 v16, v16, v75, v76
	v_max3_f32 v2, v2, v93, v94
	v_max3_f32 v16, v16, v77, v78
	v_max3_f32 v2, v2, v95, v96
	v_max3_f32 v16, v16, v79, v80
	v_max3_f32 v2, v2, v97, v81
	v_max_f32_e32 v2, v2, v16
	v_mov_b32_e32 v16, v2
	s_nop 1
	v_permlane32_swap_b32_e32 v2, v16
	v_max_f32_e32 v16, v2, v16
	s_cbranch_scc0 .LBB0_1121
	v_cmp_lt_f32_e32 vcc, s21, v16
	s_mov_b64 s[50:51], 0
	s_mov_b64 s[48:49], 0
	s_cbranch_vccnz .Lmla_rare_1
.LBB0_1118:
	v_exp_f32_e32 v17, v66
	v_exp_f32_e32 v82, v82
	v_exp_f32_e32 v66, v67
	v_exp_f32_e32 v83, v83
	v_exp_f32_e32 v67, v68
	v_exp_f32_e32 v84, v84
	v_exp_f32_e32 v68, v69
	v_exp_f32_e32 v85, v85
	v_add_f32_e32 v2, v82, v17
	v_exp_f32_e32 v69, v70
	v_exp_f32_e32 v86, v86
	v_add_f32_e32 v16, v83, v66
	v_exp_f32_e32 v70, v71
	v_exp_f32_e32 v87, v87
	v_add_f32_e32 v2, v16, v2
	v_add_f32_e32 v16, v84, v67
	v_exp_f32_e32 v71, v72
	v_exp_f32_e32 v88, v88
	v_add_f32_e32 v2, v16, v2
	v_add_f32_e32 v16, v85, v68
	v_exp_f32_e32 v72, v73
	v_exp_f32_e32 v89, v89
	v_add_f32_e32 v2, v16, v2
	v_add_f32_e32 v16, v86, v69
	v_exp_f32_e32 v73, v74
	v_exp_f32_e32 v90, v90
	v_add_f32_e32 v2, v16, v2
	v_add_f32_e32 v16, v87, v70
	v_exp_f32_e32 v74, v75
	v_exp_f32_e32 v91, v91
	v_add_f32_e32 v2, v16, v2
	v_add_f32_e32 v16, v88, v71
	v_exp_f32_e32 v75, v76
	v_exp_f32_e32 v92, v92
	v_add_f32_e32 v2, v16, v2
	v_add_f32_e32 v16, v89, v72
	v_exp_f32_e32 v76, v77
	v_exp_f32_e32 v93, v93
	v_add_f32_e32 v2, v16, v2
	v_add_f32_e32 v16, v90, v73
	v_exp_f32_e32 v77, v78
	v_exp_f32_e32 v94, v94
	v_add_f32_e32 v2, v16, v2
	v_add_f32_e32 v16, v91, v74
	v_exp_f32_e32 v78, v79
	v_exp_f32_e32 v95, v95
	v_add_f32_e32 v2, v16, v2
	v_add_f32_e32 v16, v92, v75
	v_exp_f32_e32 v79, v80
	v_exp_f32_e32 v96, v96
	v_add_f32_e32 v2, v16, v2
	v_add_f32_e32 v16, v93, v76
	v_exp_f32_e32 v80, v81
	v_exp_f32_e32 v81, v97
	v_add_f32_e32 v2, v16, v2
	v_add_f32_e32 v16, v94, v77
	v_add_f32_e32 v2, v16, v2
	v_add_f32_e32 v16, v95, v78
	v_add_f32_e32 v2, v16, v2
	v_add_f32_e32 v16, v96, v79
	v_add_f32_e32 v2, v16, v2
	v_add_f32_e32 v16, v81, v80
	v_add_f32_e32 v2, v16, v2
	s_waitcnt lgkmcnt(0)
	v_cvt_pk_bf16_f32 v66, v17, v66
	v_cvt_pk_bf16_f32 v67, v67, v68
	v_cvt_pk_bf16_f32 v68, v69, v70
	v_cvt_pk_bf16_f32 v69, v71, v72
	v_cvt_pk_bf16_f32 v70, v73, v74
	v_cvt_pk_bf16_f32 v71, v75, v76
	v_cvt_pk_bf16_f32 v72, v77, v78
	v_cvt_pk_bf16_f32 v73, v79, v80
	v_cvt_pk_bf16_f32 v74, v82, v83
	v_cvt_pk_bf16_f32 v75, v84, v85
	v_cvt_pk_bf16_f32 v76, v86, v87
	v_cvt_pk_bf16_f32 v77, v88, v89
	v_cvt_pk_bf16_f32 v78, v90, v91
	v_cvt_pk_bf16_f32 v79, v92, v93
	v_cvt_pk_bf16_f32 v80, v94, v95
	v_cvt_pk_bf16_f32 v81, v96, v81
	v_mfma_f32_32x32x16_bf16 v[34:49], v[146:149], v[66:69], v[34:49]
	s_andn2_b64 vcc, exec, s[40:41]
	s_waitcnt vmcnt(0)
	s_barrier
	v_mfma_f32_32x32x16_bf16 v[18:33], v[150:153], v[66:69], v[18:33]
	v_mfma_f32_32x32x16_bf16 v[34:49], v[138:141], v[70:73], v[34:49]
	v_mfma_f32_32x32x16_bf16 v[18:33], v[142:145], v[70:73], v[18:33]
	v_mfma_f32_32x32x16_bf16 v[34:49], v[12:15], v[74:77], v[34:49]
	v_mfma_f32_32x32x16_bf16 v[18:33], v[134:137], v[74:77], v[18:33]
	v_mfma_f32_32x32x16_bf16 v[34:49], v[8:11], v[78:81], v[34:49]
	v_mfma_f32_32x32x16_bf16 v[18:33], v[4:7], v[78:81], v[18:33]
	s_cbranch_vccnz .LBB0_1106
	s_mul_i32 s46, s58, 0x3400
	s_mul_i32 s28, s58, 0x3000
	s_add_u32 s28, s28, 0x9c00
	s_lshl_b32 s101, s100, 10
	s_add_u32 m0, s46, s101
	s_nop 0
	global_load_lds_dwordx4 v200, s[24:25]
	v_add_u32_e32 v200, v200, v201
	s_cmp_lt_u32 s100, 5
	s_cbranch_scc0 .Lmd_skb0
	s_add_u32 m0, m0, 0x2000
	s_nop 0
	global_load_lds_dwordx4 v202, s[24:25]
	v_add_u32_e32 v202, v202, v203
